# fast path v11: post-barrier LDS reads staggered (tile-A K fragments first, remaining 12 reads as fillers of tile-A QK MFMAs)
# speedup vs baseline: 1.0067x; 1.0067x over previous
; #define MFMA32(a, b, c) __builtin_amdgcn_mfma_f32_32x32x16_bf16((a), (b), (c), 0, 0, 0)
; DI unsigned pk_bf16(float lo, float hi) { f32x2 v = {lo, hi}; bf16v2 b = __builtin_convertvector(v, bf16v2); return __builtin_bit_cast(unsigned, b); }
; DI int crow(int r, int h) { return (r & 3) + 8 * (r >> 2) + 4 * h; }
; DI void attn_item(const Params& p, int g, int seq, int hd, int qt, int m, char* smem, int split_j, int sub) {
;     ...
;     bf16x8 kf[4], vf[2][4];
; #pragma unroll
;     for (int s = 0; s < 4; ++s) kf[s] = *(const bf16x8*)(Kb + l31 * 72 + s * 16 + h * 8);
; #pragma unroll
;     for (int s2 = 0; s2 < 2; ++s2)
; #pragma unroll
;       for (int dt = 0; dt < 4; ++dt) vf[s2][dt] = *(const bf16x8*)(Vb + (dt * 32 + l31) * 40 + s2 * 16 + h * 8);
;     __builtin_amdgcn_sched_barrier(0);
;     f32x16 X;
; #pragma unroll
;     for (int r = 0; r < 16; ++r) X[r] = 0.f;
; #pragma unroll
;     for (int s = 0; s < 4; ++s) X = MFMA32(kf[s], qf[s], X);
;     if (farL || farR) {
; #pragma unroll
;       for (int r = 0; r < 16; ++r) X[r] = __builtin_amdgcn_exp2f(X[r]);
;     } else {
;       const int rel0 = k0 - (qw0 + l31) + 128;
; #pragma unroll
;       for (int r = 0; r < 16; ++r) { int idx = rel0 + crow(r, h); idx = idx < 0 ? 0 : (idx > 256 ? 256 : idx); X[r] = __builtin_amdgcn_exp2f(X[r] + tab[idx]); }
;     }
;     bf16x8 pf[2];
; #pragma unroll
;     for (int s2 = 0; s2 < 2; ++s2) {
;       u32x4 w; w.x = pk_bf16(X[8 * s2], X[8 * s2 + 1]); w.y = pk_bf16(X[8 * s2 + 2], X[8 * s2 + 3]); w.z = pk_bf16(X[8 * s2 + 4], X[8 * s2 + 5]); w.w = pk_bf16(X[8 * s2 + 6], X[8 * s2 + 7]);
;       ls2 += (f32x2){X[8 * s2], X[8 * s2 + 1]}; ls2 += (f32x2){X[8 * s2 + 2], X[8 * s2 + 3]};
;       ls2 += (f32x2){X[8 * s2 + 4], X[8 * s2 + 5]}; ls2 += (f32x2){X[8 * s2 + 6], X[8 * s2 + 7]};
;       pf[s2] = __builtin_bit_cast(bf16x8, w);
;     }
; #pragma unroll
;     for (int s2 = 0; s2 < 2; ++s2)
; #pragma unroll
;       for (int dt = 0; dt < 4; ++dt) O[dt] = MFMA32(pf[s2], vf[s2][dt], O[dt]);
.Lat2_reads:
	ds_read_b128 v[64:67], v192
	ds_read_b128 v[80:83], v192 offset:32
	ds_read_b128 v[84:87], v192 offset:64
	ds_read_b128 v[88:91], v192 offset:96
	s_waitcnt lgkmcnt(3)
	v_mfma_f32_32x32x16_bf16 v[64:79], v[64:67], v[104:107], 0
	ds_read_b128 v[220:223], v192 offset:4608
	ds_read_b128 v[224:227], v192 offset:4640
	ds_read_b128 v[236:239], v192 offset:4672
	ds_read_b128 v[240:243], v192 offset:4704
	s_waitcnt lgkmcnt(6)
	v_mfma_f32_32x32x16_bf16 v[64:79], v[80:83], v[108:111], v[64:79]
	ds_read_b128 v[156:159], v244 offset:18432
	ds_read_b128 v[160:163], v244 offset:20992
	s_waitcnt lgkmcnt(7)
	v_mfma_f32_32x32x16_bf16 v[64:79], v[84:87], v[112:115], v[64:79]
	ds_read_b128 v[164:167], v244 offset:23552
	ds_read_b128 v[152:155], v244 offset:26112
	s_waitcnt lgkmcnt(8)
	v_mfma_f32_32x32x16_bf16 v[64:79], v[88:91], v[116:119], v[64:79]
	ds_read_b128 v[148:151], v244 offset:18464
	ds_read_b128 v[144:147], v244 offset:21024
	ds_read_b128 v[136:139], v244 offset:23584
	ds_read_b128 v[140:143], v244 offset:26144
	s_waitcnt lgkmcnt(11)
	v_mfma_f32_32x32x16_bf16 v[80:95], v[220:223], v[104:107], 0
	s_waitcnt lgkmcnt(10)
	v_mfma_f32_32x32x16_bf16 v[80:95], v[224:227], v[108:111], v[80:95]
	v_exp_f32_e32 v64, v64
	v_exp_f32_e32 v65, v65
	v_exp_f32_e32 v66, v66
	v_exp_f32_e32 v67, v67
	v_exp_f32_e32 v68, v68
	v_exp_f32_e32 v69, v69
	s_waitcnt lgkmcnt(9)
	v_mfma_f32_32x32x16_bf16 v[80:95], v[236:239], v[112:115], v[80:95]
	v_exp_f32_e32 v70, v70
	v_exp_f32_e32 v71, v71
	v_exp_f32_e32 v72, v72
	v_exp_f32_e32 v73, v73
	v_exp_f32_e32 v74, v74
	v_exp_f32_e32 v75, v75
	s_waitcnt lgkmcnt(8)
	v_mfma_f32_32x32x16_bf16 v[80:95], v[240:243], v[116:119], v[80:95]
	v_exp_f32_e32 v76, v76
	v_exp_f32_e32 v77, v77
	v_exp_f32_e32 v78, v78
	v_exp_f32_e32 v79, v79
	v_cvt_pk_bf16_f32 v220, v64, v65
	v_cvt_pk_bf16_f32 v221, v66, v67
	v_cvt_pk_bf16_f32 v222, v68, v69
	v_cvt_pk_bf16_f32 v223, v70, v71
	v_cvt_pk_bf16_f32 v224, v72, v73
	v_cvt_pk_bf16_f32 v225, v74, v75
	v_cvt_pk_bf16_f32 v226, v76, v77
	v_cvt_pk_bf16_f32 v227, v78, v79
	s_waitcnt lgkmcnt(7)
	v_mfma_f32_32x32x16_bf16 v[48:63], v[220:223], v[156:159], v[48:63]
	ds_read_b128 v[156:159], v244 offset:28672
	v_exp_f32_e32 v80, v80
	v_exp_f32_e32 v81, v81
	v_exp_f32_e32 v82, v82
	s_waitcnt lgkmcnt(7)
	v_mfma_f32_32x32x16_bf16 v[32:47], v[220:223], v[160:163], v[32:47]
	ds_read_b128 v[160:163], v244 offset:31232
	v_exp_f32_e32 v83, v83
	v_exp_f32_e32 v84, v84
	v_exp_f32_e32 v85, v85
	s_waitcnt lgkmcnt(7)
	v_mfma_f32_32x32x16_bf16 v[16:31], v[220:223], v[164:167], v[16:31]
	ds_read_b128 v[164:167], v244 offset:33792
	v_exp_f32_e32 v86, v86
	v_exp_f32_e32 v87, v87
	v_exp_f32_e32 v88, v88
	s_waitcnt lgkmcnt(7)
	v_mfma_f32_32x32x16_bf16 v[0:15], v[220:223], v[152:155], v[0:15]
	ds_read_b128 v[152:155], v244 offset:36352
	v_exp_f32_e32 v89, v89
	v_exp_f32_e32 v90, v90
	v_exp_f32_e32 v91, v91
	s_waitcnt lgkmcnt(7)
	v_mfma_f32_32x32x16_bf16 v[48:63], v[224:227], v[148:151], v[48:63]
	ds_read_b128 v[148:151], v244 offset:28704
	v_exp_f32_e32 v92, v92
	v_exp_f32_e32 v93, v93
	v_exp_f32_e32 v94, v94
	v_exp_f32_e32 v95, v95
	s_waitcnt lgkmcnt(7)
	v_mfma_f32_32x32x16_bf16 v[32:47], v[224:227], v[144:147], v[32:47]
	ds_read_b128 v[144:147], v244 offset:31264
	v_cvt_pk_bf16_f32 v236, v80, v81
	v_cvt_pk_bf16_f32 v237, v82, v83
	v_cvt_pk_bf16_f32 v238, v84, v85
	v_add_f32_e32 v246, v66, v70
	v_add_f32_e32 v247, v67, v71
	v_add_f32_e32 v186, v186, v64
	v_add_f32_e32 v187, v187, v65
	s_waitcnt lgkmcnt(7)
	v_mfma_f32_32x32x16_bf16 v[16:31], v[224:227], v[136:139], v[16:31]
	ds_read_b128 v[136:139], v244 offset:33824
	v_cvt_pk_bf16_f32 v239, v86, v87
	v_cvt_pk_bf16_f32 v240, v88, v89
	v_cvt_pk_bf16_f32 v241, v90, v91
	v_add_f32_e32 v246, v246, v74
	v_add_f32_e32 v247, v247, v75
	v_add_f32_e32 v186, v186, v68
	v_add_f32_e32 v187, v187, v69
	s_waitcnt lgkmcnt(7)
	v_mfma_f32_32x32x16_bf16 v[0:15], v[224:227], v[140:143], v[0:15]
	ds_read_b128 v[140:143], v244 offset:36384
	v_cvt_pk_bf16_f32 v242, v92, v93
	v_cvt_pk_bf16_f32 v243, v94, v95
	v_add_f32_e32 v246, v246, v78
	v_add_f32_e32 v247, v247, v79
	v_add_f32_e32 v186, v186, v72
	v_add_f32_e32 v187, v187, v73
	s_andn2_b64 vcc, exec, s[8:9]
	s_cbranch_vccnz .Lat2_pvplain
; #define MFMA32(a, b, c) __builtin_amdgcn_mfma_f32_32x32x16_bf16((a), (b), (c), 0, 0, 0)
; DI unsigned pk_bf16(float lo, float hi) { f32x2 v = {lo, hi}; bf16v2 b = __builtin_convertvector(v, bf16v2); return __builtin_bit_cast(unsigned, b); }
; DI void attn_item(const Params& p, int g, int seq, int hd, int qt, int m, char* smem, int split_j, int sub) {
;     ...
;     bf16x8 pf[2];
; #pragma unroll
;     for (int s2 = 0; s2 < 2; ++s2) {
;       u32x4 w; w.x = pk_bf16(X[8 * s2], X[8 * s2 + 1]); w.y = pk_bf16(X[8 * s2 + 2], X[8 * s2 + 3]); w.z = pk_bf16(X[8 * s2 + 4], X[8 * s2 + 5]); w.w = pk_bf16(X[8 * s2 + 6], X[8 * s2 + 7]);
;       ls2 += (f32x2){X[8 * s2], X[8 * s2 + 1]}; ls2 += (f32x2){X[8 * s2 + 2], X[8 * s2 + 3]};
;       ls2 += (f32x2){X[8 * s2 + 4], X[8 * s2 + 5]}; ls2 += (f32x2){X[8 * s2 + 6], X[8 * s2 + 7]};
;       pf[s2] = __builtin_bit_cast(bf16x8, w);
;     }
; #pragma unroll
;     for (int s2 = 0; s2 < 2; ++s2)
; #pragma unroll
;       for (int dt = 0; dt < 4; ++dt) O[dt] = MFMA32(pf[s2], vf[s2][dt], O[dt]);
;   };
;   load_tile(0, rkA, rvA0, rvA1);
;   load_tile(1, rkB, rvB0, rvB1);
;   __syncthreads();
;   store_tile(0, rkA, rvA0, rvA1);
;   store_tile(1, rkB, rvB0, rvB1);
;   __syncthreads();
;   for (int it = 0; it < npairs; ++it) {
;     const int set = it & 1;
;     if (it + 1 < npairs) { load_tile(2 * it + 2, rkA, rvA0, rvA1); load_tile(2 * it + 3, rkB, rvB0, rvB1); }
;     compute(2 * it, 2 * set);
;     compute(2 * it + 1, 2 * set + 1);
;     if (it + 1 < npairs) { store_tile(2 * (set ^ 1), rkA, rvA0, rvA1); store_tile(2 * (set ^ 1) + 1, rkB, rvB0, rvB1); }
;     __syncthreads();
;   }
	s_add_i32 s10, s15, 1
	s_cmp_lt_u32 s10, s73
	s_cbranch_scc0 .Lat2_pvw
	s_xor_b32 s7, s16, 2
	s_mul_i32 s8, s7, 0x2800
	s_add_i32 s8, s8, 32
	s_mulk_i32 s7, 0x1200
	v_add_u32_e32 v192, s7, v169
	v_add3_u32 v244, s8, v189, v190
	s_addk_i32 s8, 0x2800
	s_add_i32 s13, s13, 64
	s_add_i32 s6, s6, 2
	s_mov_b32 s15, s10
	s_mov_b64 s[20:21], 0x1000
	s_waitcnt lgkmcnt(7)
	v_mfma_f32_32x32x16_bf16 v[48:63], v[236:239], v[156:159], v[48:63]
	s_waitcnt vmcnt(5)
	ds_write_b128 v192, v[96:99]
	s_add_i32 s50, s6, -1
	s_lshl_b64 s[10:11], s[50:51], 12
	v_lshl_add_u64 v[220:221], v[172:173], 0, s[10:11]
	v_add_f32_e32 v186, v186, v76
	v_add_f32_e32 v187, v187, v77
	s_waitcnt lgkmcnt(7)
	v_mfma_f32_32x32x16_bf16 v[32:47], v[236:239], v[160:163], v[32:47]
	s_waitcnt vmcnt(4)
	ds_write_b128 v244, v[100:103] offset:18432
	global_load_dwordx4 v[96:99], v[220:221], off
	s_lshl_b64 s[10:11], s[50:51], 13
	v_lshl_add_u64 v[222:223], v[170:171], 0, s[10:11]
	v_add_f32_e32 v186, v186, v246
	v_add_f32_e32 v187, v187, v247
	s_waitcnt lgkmcnt(7)
	v_mfma_f32_32x32x16_bf16 v[16:31], v[236:239], v[164:167], v[16:31]
	s_waitcnt vmcnt(4)
	ds_write_b128 v244, v[120:123] offset:23552
	global_load_dwordx4 v[100:103], v[222:223], off
	v_lshl_add_u64 v[224:225], v[222:223], 0, s[20:21]
	v_add_f32_e32 v246, v82, v86
	v_add_f32_e32 v247, v83, v87
	v_add_f32_e32 v186, v186, v80
	s_waitcnt lgkmcnt(7)
	v_mfma_f32_32x32x16_bf16 v[0:15], v[236:239], v[152:155], v[0:15]
	s_waitcnt vmcnt(4)
	ds_write_b128 v192, v[124:127] offset:4608
	global_load_dwordx4 v[120:123], v[224:225], off
	s_mov_b32 s7, s51
	s_lshl_b64 s[10:11], s[6:7], 12
	v_lshl_add_u64 v[220:221], v[172:173], 0, s[10:11]
	v_add_f32_e32 v187, v187, v81
	v_add_f32_e32 v246, v246, v90
	v_add_f32_e32 v247, v247, v91
	s_waitcnt lgkmcnt(7)
	v_mfma_f32_32x32x16_bf16 v[48:63], v[240:243], v[148:151], v[48:63]
	v_add3_u32 v192, s8, v189, v190
	s_waitcnt vmcnt(4)
	ds_write_b128 v192, v[128:131] offset:18432
	global_load_dwordx4 v[124:127], v[220:221], off
	s_lshl_b64 s[10:11], s[6:7], 13
	v_lshl_add_u64 v[222:223], v[170:171], 0, s[10:11]
	v_add_f32_e32 v186, v186, v84
	v_add_f32_e32 v187, v187, v85
	v_add_f32_e32 v246, v246, v94
	s_waitcnt lgkmcnt(7)
	v_mfma_f32_32x32x16_bf16 v[32:47], v[240:243], v[144:147], v[32:47]
	s_waitcnt vmcnt(4)
	ds_write_b128 v192, v[132:135] offset:23552
	global_load_dwordx4 v[128:131], v[222:223], off
	v_lshl_add_u64 v[224:225], v[222:223], 0, s[20:21]
	v_add_f32_e32 v247, v247, v95
	v_add_f32_e32 v186, v186, v88
	v_add_f32_e32 v187, v187, v89
	s_waitcnt lgkmcnt(7)
	v_mfma_f32_32x32x16_bf16 v[16:31], v[240:243], v[136:139], v[16:31]
	global_load_dwordx4 v[132:135], v[224:225], off
	v_add_f32_e32 v186, v186, v92
	v_add_f32_e32 v187, v187, v93
	s_add_i32 s7, s14, s13
	s_cmpk_lt_i32 s7, 0xff42
	s_cselect_b32 s19, 1, 0
	s_cmpk_gt_i32 s7, 0x9e
	s_cselect_b32 s50, 1, 0
	s_cmp_eq_u32 s17, 2
	s_cselect_b32 s50, s50, 0
	s_or_b32 s19, s19, s50
	s_waitcnt lgkmcnt(6)
	v_mfma_f32_32x32x16_bf16 v[0:15], v[240:243], v[140:143], v[0:15]
	v_add_f32_e32 v186, v186, v246
	v_add_f32_e32 v187, v187, v247
	s_mov_b64 s[8:9], -1
	s_add_i32 s10, s6, -3
	s_and_b32 s16, s10, 2
	s_mul_i32 s10, s16, 0x1200
	s_mul_i32 s18, s16, 0x2800
	v_add_u32_e32 v192, s10, v191
	v_add_u32_e32 v244, s18, v196
	s_cmp_lg_u32 s19, 0
	s_waitcnt lgkmcnt(0)
	s_barrier
	s_cbranch_scc1 .Lat2_reads
	s_branch .LBB0_319
